# attention loops: start S(kt0) MFMA chain right after the barrier; tile j+1 LDS stores and tile j+2 global loads moved behind it (on top of v17)
# baseline (speedup 1.0000x reference)
; #define LAS __attribute__((address_space(3)))
; DI int crow(int i, int hh) { return (i & 3) + 8 * (i >> 2) + 4 * hh; }
; #define MFMA32(a, b, c) __builtin_amdgcn_mfma_f32_32x32x16_bf16((a), (b), (c), 0, 0, 0)
; DI void attn_store(LAS unsigned char* lds, int tid, const u32x4 (&kr)[3], const u32x4 (&vr)[2]) {
;     LAS bf16_t* Ks = (LAS bf16_t*)(lds + AT_KS); LAS bf16_t* Rs = (LAS bf16_t*)(lds + AT_RS); LAS bf16_t* Vs = (LAS bf16_t*)(lds + AT_VS);
; #pragma unroll
;     for (int i = 0; i < 2; ++i) { const int ck = tid + 512 * i, row = ck >> 4, cc = ck & 15; *(LAS u32x4*)(Ks + row * 136 + 8 * cc) = kr[i]; }
;     { const int row = tid >> 3, cc = tid & 7; *(LAS u32x4*)(Rs + row * 72 + 8 * cc) = kr[2]; }
; #pragma unroll
;     for (int i = 0; i < 2; ++i) { const int cv = tid + 512 * i, v = cv >> 3, cc = cv & 7;
;         LAS bf16_t* d = Vs + v * 72 + 16 * (cc >> 1) + 4 * (cc & 1);
;         *(LAS u32x2*)d = (u32x2){vr[i].x, vr[i].y}; *(LAS u32x2*)(d + 8) = (u32x2){vr[i].z, vr[i].w}; }
; DI void attn_item(CArgs& a, LAS unsigned char* lds, int l, int b, int h, int qb, int tid_, int wave, int lane_) {
;     ...
;     for (int j = 0; j < NT; ++j) {
;         const int boff = (j & 1) * AT_BUF;
;         if (j + 1 < NT) attn_store(lds + (AT_BUF - boff), tid, kr, vr);
;         if (j + 2 < NT) attn_load(a, b, h, j + 2, F, kr, vr);
;         LAS bf16_t* Ks = (LAS bf16_t*)(lds + boff + AT_KS); LAS bf16_t* Rs = (LAS bf16_t*)(lds + boff + AT_RS); LAS bf16_t* Vs = (LAS bf16_t*)(lds + boff + AT_VS);
; #pragma unroll
;         for (int kt = 0; kt < 2; ++kt) {
;             f32x16 p = zero16();
; #pragma unroll
;             for (int ks = 0; ks < 8; ++ks) p = MFMA32(lds_b128(Ks + (32 * kt + r) * 136 + 16 * ks + 8 * hh), qf[ks], p);
; #pragma unroll
;             for (int ks = 0; ks < 4; ++ks) p = MFMA32(lds_b128(Rs + (32 * kt + r) * 72 + 16 * ks + 8 * hh), qf[8 + ks], p);
;             if (j >= 4 * qb) {
; #pragma unroll
;                 for (int i = 0; i < 16; ++i) { const int key = 64 * j + 32 * kt + crow(i, hh); if (key > qloc) p[i] = -INFINITY; } }
.LBB0_296:
	s_bitcmp1_b32 s4, 0
	s_cselect_b32 s0, 0xb000, 0
	s_add_i32 s55, s4, 1
	s_add_i32 s56, s0, 0
	v_add_u32_e32 v205, s56, v80
	v_add_u32_e32 v209, v205, v200
	v_add_u32_e32 v210, v205, v199
	ds_read_b128 v[212:215], v209
	ds_read_b128 v[226:229], v209 offset:32
	ds_read_b128 v[230:233], v209 offset:64
	ds_read_b128 v[234:237], v209 offset:96
	s_sub_i32 s100, 0, s0
	s_add_i32 s101, s100, 0xb000
	s_cmp_ge_u32 s4, s51
	s_cselect_b64 s[0:1], -1, 0
	s_cmp_lt_u32 s4, s51
	v_add_u32_e32 v208, s36, v195
	s_waitcnt lgkmcnt(3)
	v_mfma_f32_32x32x16_bf16 v[64:79], v[212:215], v[98:101], 0
	ds_read_b128 v[212:215], v209 offset:128
	s_waitcnt lgkmcnt(3)
	v_mfma_f32_32x32x16_bf16 v[64:79], v[226:229], v[102:105], v[64:79]
	ds_read_b128 v[226:229], v209 offset:160
	s_waitcnt lgkmcnt(3)
	v_mfma_f32_32x32x16_bf16 v[64:79], v[230:233], v[106:109], v[64:79]
	ds_read_b128 v[230:233], v209 offset:192
	s_waitcnt lgkmcnt(3)
	v_mfma_f32_32x32x16_bf16 v[64:79], v[234:237], v[110:113], v[64:79]
	ds_read_b128 v[234:237], v209 offset:224
	s_waitcnt lgkmcnt(3)
	v_mfma_f32_32x32x16_bf16 v[64:79], v[212:215], v[114:117], v[64:79]
	ds_read_b128 v[212:215], v210 offset:17408
	s_waitcnt lgkmcnt(3)
	v_mfma_f32_32x32x16_bf16 v[64:79], v[226:229], v[118:121], v[64:79]
	ds_read_b128 v[226:229], v210 offset:17440
	s_waitcnt lgkmcnt(3)
	v_mfma_f32_32x32x16_bf16 v[64:79], v[230:233], v[122:125], v[64:79]
	ds_read_b128 v[230:233], v210 offset:17472
	s_waitcnt lgkmcnt(3)
	v_mfma_f32_32x32x16_bf16 v[64:79], v[234:237], v[126:129], v[64:79]
	ds_read_b128 v[234:237], v210 offset:17504
	s_waitcnt lgkmcnt(3)
	v_mfma_f32_32x32x16_bf16 v[64:79], v[212:215], v[130:133], v[64:79]
	s_waitcnt lgkmcnt(2)
	v_mfma_f32_32x32x16_bf16 v[64:79], v[226:229], v[138:141], v[64:79]
	s_waitcnt lgkmcnt(1)
	v_mfma_f32_32x32x16_bf16 v[64:79], v[230:233], v[134:137], v[64:79]
	s_waitcnt lgkmcnt(0)
	v_mfma_f32_32x32x16_bf16 v[64:79], v[234:237], v[142:145], v[64:79]
	s_cmp_ge_u32 s55, s54
	s_cbranch_scc1 .LBB0_298
	v_lshl_add_u32 v230, v188, 1, s100
	v_add_u32_e32 v231, v230, v175
	v_add_u32_e32 v230, v230, v189
	s_waitcnt vmcnt(4)
	ds_write_b128 v231, v[146:149] offset:45056
	s_waitcnt vmcnt(3)
	ds_write_b128 v230, v[150:153] offset:45056
	v_add3_u32 v230, s100, v190, v191
	s_waitcnt vmcnt(2)
	ds_write_b128 v230, v[154:157] offset:62464
	v_add3_u32 v230, s101, v192, v193
	v_add_u32_e32 v231, v230, v190
	v_add_u32_e32 v230, v230, v194
	v_add_u32_e32 v231, 0x6800, v231
	v_add_u32_e32 v230, 0x6800, v230
	s_waitcnt vmcnt(1)
	ds_write2_b64 v231, v[158:159], v[160:161] offset1:2
	s_waitcnt vmcnt(0)
	ds_write2_b64 v230, v[162:163], v[164:165] offset1:2
.LBB0_298:
	s_add_i32 s100, s4, 2
	s_cmp_ge_u32 s100, s54
	s_cbranch_scc1 .LBB0_300
	v_lshl_add_u64 v[226:227], s[44:45], 0, v[182:183]
	v_lshl_add_u64 v[228:229], s[44:45], 0, v[184:185]
	global_load_dwordx4 v[146:149], v[226:227], off
	global_load_dwordx4 v[150:153], v[228:229], off
	v_lshl_add_u64 v[226:227], s[44:45], 0, v[180:181]
	v_lshl_add_u64 v[228:229], s[44:45], 0, v[176:177]
	global_load_dwordx4 v[154:157], v[226:227], off
	global_load_dwordx4 v[158:161], v[228:229], off
	v_lshl_add_u64 v[226:227], s[44:45], 0, v[178:179]
	global_load_dwordx4 v[162:165], v[226:227], off
.LBB0_300:
	ds_read_b128 v[216:219], v209 offset:8704
	ds_read_b128 v[238:241], v209 offset:8736
	ds_read_b128 v[242:245], v209 offset:8768
	ds_read_b128 v[246:249], v209 offset:8800
	s_nop 3
	s_cmp_lt_u32 s4, s51
	s_cbranch_scc1 .LBB0_302
	v_cmp_lt_i32_e32 vcc, v208, v174
	v_add_u32_e32 v205, 2, v208
	s_nop 0
	v_cndmask_b32_e32 v65, v223, v65, vcc
	v_cmp_le_i32_e32 vcc, v208, v174
	s_nop 1
	v_cndmask_b32_e32 v64, v223, v64, vcc
	v_cmp_le_i32_e32 vcc, v205, v174
	v_add_u32_e32 v205, 3, v208
	s_nop 0
	v_cndmask_b32_e32 v66, v223, v66, vcc
	v_cmp_le_i32_e32 vcc, v205, v174
	v_add_u32_e32 v205, 8, v208
	s_nop 0
	v_cndmask_b32_e32 v67, v223, v67, vcc
	v_cmp_le_i32_e32 vcc, v205, v174
	v_add_u32_e32 v205, 9, v208
	s_nop 0
	v_cndmask_b32_e32 v68, v223, v68, vcc
	v_cmp_le_i32_e32 vcc, v205, v174
	v_add_u32_e32 v205, 10, v208
	s_nop 0
	v_cndmask_b32_e32 v69, v223, v69, vcc
	v_cmp_le_i32_e32 vcc, v205, v174
	v_add_u32_e32 v205, 11, v208
	s_nop 0
	v_cndmask_b32_e32 v70, v223, v70, vcc
	v_cmp_le_i32_e32 vcc, v205, v174
	v_add_u32_e32 v205, 16, v208
	s_nop 0
	v_cndmask_b32_e32 v71, v223, v71, vcc
	v_cmp_le_i32_e32 vcc, v205, v174
	v_add_u32_e32 v205, 17, v208
	s_nop 0
	v_cndmask_b32_e32 v72, v223, v72, vcc
	v_cmp_le_i32_e32 vcc, v205, v174
	v_add_u32_e32 v205, 18, v208
	s_nop 0
	v_cndmask_b32_e32 v73, v223, v73, vcc
	v_cmp_le_i32_e32 vcc, v205, v174
	v_add_u32_e32 v205, 19, v208
	s_nop 0
	v_cndmask_b32_e32 v74, v223, v74, vcc
	v_cmp_le_i32_e32 vcc, v205, v174
	v_add_u32_e32 v205, 24, v208
	s_nop 0
	v_cndmask_b32_e32 v75, v223, v75, vcc
	v_cmp_le_i32_e32 vcc, v205, v174
	v_add_u32_e32 v205, 25, v208
	s_nop 0
	v_cndmask_b32_e32 v76, v223, v76, vcc
	v_cmp_le_i32_e32 vcc, v205, v174
	v_add_u32_e32 v205, 26, v208
	s_nop 0
	v_cndmask_b32_e32 v77, v223, v77, vcc
	v_cmp_le_i32_e32 vcc, v205, v174
	v_add_u32_e32 v205, 27, v208
	s_nop 0
	v_cndmask_b32_e32 v78, v223, v78, vcc
	v_cmp_le_i32_e32 vcc, v205, v174
	s_nop 1
	v_cndmask_b32_e32 v79, v223, v79, vcc
; DI float shx(float v, int o, int lane) { return __int_as_float(__builtin_amdgcn_ds_bpermute((lane ^ o) << 2, __float_as_int(v))); }
; DI int crow(int i, int hh) { return (i & 3) + 8 * (i >> 2) + 4 * hh; }
; DI void attn_item(CArgs& a, LAS unsigned char* lds, int l, int b, int h, int qb, int tid_, int wave, int lane_) {
;     ...
;             float tmax = p[0];
; #pragma unroll
;             for (int i = 1; i < 16; ++i) tmax = fmaxf(tmax, p[i]);
;             tmax = fmaxf(tmax, shx(tmax, 32, lane));
;             const float m_new = fmaxf(m_run, tmax), alpha = __builtin_amdgcn_exp2f(m_run - m_new); m_run = m_new;
;             float rsum = 0.f;
; #pragma unroll
;             for (int i = 0; i < 16; ++i) { const float e = __builtin_amdgcn_exp2f(p[i] - m_new); p[i] = e; rsum += e; }
;             l_run = l_run * alpha + rsum;
;             if (__any(alpha != 1.f)) {
;                 if (hh == 0) scr[r] = alpha;
;                 asm volatile("s_waitcnt lgkmcnt(0)" ::: "memory");
; #pragma unroll
;                 for (int i = 0; i < 16; ++i) { const float ai = scr[crow(i, hh)]; o[0][i] *= ai; o[1][i] *= ai; o[2][i] *= ai; o[3][i] *= ai; }
;             }
.LBB0_302:
	v_max_f32_e32 v205, v65, v65
	v_max_f32_e32 v206, v64, v64
	v_max_f32_e32 v205, v206, v205
	v_max3_f32 v205, v205, v66, v67
	v_max3_f32 v205, v205, v68, v69
	v_max3_f32 v205, v205, v70, v71
	v_max3_f32 v205, v205, v72, v73
	v_max3_f32 v205, v205, v74, v75
	v_max3_f32 v205, v205, v76, v77
	v_max3_f32 v205, v205, v78, v79
	ds_bpermute_b32 v206, v198, v205
	s_waitcnt lgkmcnt(4)
	v_mfma_f32_32x32x16_bf16 v[82:97], v[216:219], v[98:101], 0
	ds_read_b128 v[216:219], v209 offset:8832
	s_waitcnt lgkmcnt(4)
	v_mfma_f32_32x32x16_bf16 v[82:97], v[238:241], v[102:105], v[82:97]
	ds_read_b128 v[238:241], v209 offset:8864
	s_waitcnt lgkmcnt(2)
	v_max3_f32 v211, v204, v205, v206
	v_sub_f32_e32 v204, v204, v211
	v_exp_f32_e32 v206, v204
	s_nop 0
	v_cmp_neq_f32_e32 vcc, 1.0, v206
	s_cbranch_vccz .LBB0_306
	s_and_saveexec_b64 s[4:5], s[6:7]
	ds_write_b32 v197, v206
	s_or_b64 exec, exec, s[4:5]
	s_waitcnt lgkmcnt(0)
	v_add_u32_e32 v204, s27, v80
	ds_read_b128 v[212:215], v204 offset:96
	ds_read_b128 v[226:229], v204 offset:64
	ds_read_b128 v[230:233], v204 offset:32
	ds_read_b128 v[234:237], v204
	s_mov_b64 s[58:59], 0x10000
	s_waitcnt lgkmcnt(3)
	v_pk_mul_f32 v[12:13], v[12:13], v[212:213]
	s_waitcnt lgkmcnt(2)
	v_pk_mul_f32 v[8:9], v[8:9], v[226:227]
	s_waitcnt lgkmcnt(1)
	v_pk_mul_f32 v[4:5], v[4:5], v[230:231]
	v_pk_mul_f32 v[14:15], v[14:15], v[214:215]
	v_pk_mul_f32 v[10:11], v[10:11], v[228:229]
	v_pk_mul_f32 v[6:7], v[6:7], v[232:233]
	s_waitcnt lgkmcnt(0)
	v_pk_mul_f32 v[2:3], v[2:3], v[236:237]
	v_pk_mul_f32 v[0:1], v[0:1], v[234:235]
	v_pk_mul_f32 v[28:29], v[28:29], v[212:213]
	v_pk_mul_f32 v[24:25], v[24:25], v[226:227]
	v_pk_mul_f32 v[20:21], v[20:21], v[230:231]
	v_pk_mul_f32 v[30:31], v[30:31], v[214:215]
	v_pk_mul_f32 v[26:27], v[26:27], v[228:229]
	v_pk_mul_f32 v[22:23], v[22:23], v[232:233]
	v_pk_mul_f32 v[18:19], v[18:19], v[236:237]
	v_pk_mul_f32 v[16:17], v[16:17], v[234:235]
	v_pk_mul_f32 v[44:45], v[44:45], v[212:213]
	v_pk_mul_f32 v[40:41], v[40:41], v[226:227]
	v_pk_mul_f32 v[36:37], v[36:37], v[230:231]
	v_pk_mul_f32 v[46:47], v[46:47], v[214:215]
	v_pk_mul_f32 v[42:43], v[42:43], v[228:229]
	v_pk_mul_f32 v[38:39], v[38:39], v[232:233]
	v_pk_mul_f32 v[34:35], v[34:35], v[236:237]
	v_pk_mul_f32 v[32:33], v[32:33], v[234:235]
	v_pk_mul_f32 v[60:61], v[60:61], v[212:213]
	v_pk_mul_f32 v[56:57], v[56:57], v[226:227]
	v_pk_mul_f32 v[52:53], v[52:53], v[230:231]
	v_pk_mul_f32 v[62:63], v[62:63], v[214:215]
	v_pk_mul_f32 v[58:59], v[58:59], v[228:229]
	v_pk_mul_f32 v[54:55], v[54:55], v[232:233]
	v_pk_mul_f32 v[50:51], v[50:51], v[236:237]
	v_pk_mul_f32 v[48:49], v[48:49], v[234:235]
; DI float shx(float v, int o, int lane) { return __int_as_float(__builtin_amdgcn_ds_bpermute((lane ^ o) << 2, __float_as_int(v))); }
; DI int crow(int i, int hh) { return (i & 3) + 8 * (i >> 2) + 4 * hh; }
; #define MFMA32(a, b, c) __builtin_amdgcn_mfma_f32_32x32x16_bf16((a), (b), (c), 0, 0, 0)
; DI void attn_item(CArgs& a, LAS unsigned char* lds, int l, int b, int h, int qb, int tid_, int wave, int lane_) {
;     ...
;         for (int kt = 0; kt < 2; ++kt) {
;             f32x16 p = zero16();
; #pragma unroll
;             for (int ks = 0; ks < 8; ++ks) p = MFMA32(lds_b128(Ks + (32 * kt + r) * 136 + 16 * ks + 8 * hh), qf[ks], p);
; #pragma unroll
;             for (int ks = 0; ks < 4; ++ks) p = MFMA32(lds_b128(Rs + (32 * kt + r) * 72 + 16 * ks + 8 * hh), qf[8 + ks], p);
;             if (j >= 4 * qb) {
; #pragma unroll
;                 for (int i = 0; i < 16; ++i) { const int key = 64 * j + 32 * kt + crow(i, hh); if (key > qloc) p[i] = -INFINITY; } }
;             float tmax = p[0];
; #pragma unroll
;             for (int i = 1; i < 16; ++i) tmax = fmaxf(tmax, p[i]);
;             tmax = fmaxf(tmax, shx(tmax, 32, lane));
;             const float m_new = fmaxf(m_run, tmax), alpha = __builtin_amdgcn_exp2f(m_run - m_new); m_run = m_new;
;             float rsum = 0.f;
; #pragma unroll
;             for (int i = 0; i < 16; ++i) { const float e = __builtin_amdgcn_exp2f(p[i] - m_new); p[i] = e; rsum += e; }
;             l_run = l_run * alpha + rsum;
;             if (__any(alpha != 1.f)) {
;                 if (hh == 0) scr[r] = alpha;
;                 asm volatile("s_waitcnt lgkmcnt(0)" ::: "memory");
; #pragma unroll
;                 for (int i = 0; i < 16; ++i) { const float ai = scr[crow(i, hh)]; o[0][i] *= ai; o[1][i] *= ai; o[2][i] *= ai; o[3][i] *= ai; }
;             }
;             const bf16x8 pa0 = packstep<0>(p), pa1 = packstep<1>(p);
; #pragma unroll
;             for (int vt = 0; vt < 4; ++vt) {
;                 o[vt] = MFMA32(pa0, lds_b128(Vs + (32 * vt + r) * 72 + 32 * kt + 8 * hh), o[vt]);
;                 o[vt] = MFMA32(pa1, lds_b128(Vs + (32 * vt + r) * 72 + 32 * kt + 16 + 8 * hh), o[vt]); }
.LBB0_306:
	v_add3_u32 v205, s56, v199, v202
	v_add3_u32 v207, s56, v201, v202
	s_waitcnt lgkmcnt(4)
	v_mfma_f32_32x32x16_bf16 v[82:97], v[242:245], v[106:109], v[82:97]
	ds_read_b128 v[242:245], v209 offset:8896
	s_waitcnt lgkmcnt(4)
	v_mfma_f32_32x32x16_bf16 v[82:97], v[246:249], v[110:113], v[82:97]
	ds_read_b128 v[246:249], v209 offset:8928
	v_sub_f32_e32 v64, v64, v211
	v_exp_f32_e32 v212, v64
	v_sub_f32_e32 v64, v65, v211
	v_exp_f32_e32 v213, v64
	v_sub_f32_e32 v64, v66, v211
	v_exp_f32_e32 v214, v64
	v_sub_f32_e32 v64, v67, v211
	v_exp_f32_e32 v215, v64
	s_waitcnt lgkmcnt(3)
	v_mfma_f32_32x32x16_bf16 v[82:97], v[216:219], v[114:117], v[82:97]
	ds_read_b128 v[216:219], v210 offset:22016
	s_waitcnt lgkmcnt(3)
	v_mfma_f32_32x32x16_bf16 v[82:97], v[238:241], v[118:121], v[82:97]
	ds_read_b128 v[238:241], v210 offset:22048
	v_sub_f32_e32 v64, v68, v211
	v_exp_f32_e32 v225, v64
	v_sub_f32_e32 v64, v69, v211
	v_exp_f32_e32 v226, v64
	v_sub_f32_e32 v64, v70, v211
	v_exp_f32_e32 v227, v64
	v_sub_f32_e32 v64, v71, v211
	v_exp_f32_e32 v228, v64
	s_waitcnt lgkmcnt(3)
	v_mfma_f32_32x32x16_bf16 v[82:97], v[242:245], v[122:125], v[82:97]
	ds_read_b128 v[242:245], v210 offset:22080
	s_waitcnt lgkmcnt(3)
	v_mfma_f32_32x32x16_bf16 v[82:97], v[246:249], v[126:129], v[82:97]
	ds_read_b128 v[246:249], v210 offset:22112
	v_sub_f32_e32 v64, v72, v211
	v_exp_f32_e32 v229, v64
	v_sub_f32_e32 v64, v73, v211
	v_exp_f32_e32 v230, v64
	v_sub_f32_e32 v64, v74, v211
	v_exp_f32_e32 v231, v64
	v_sub_f32_e32 v64, v75, v211
	v_exp_f32_e32 v232, v64
	s_waitcnt lgkmcnt(3)
	v_mfma_f32_32x32x16_bf16 v[82:97], v[216:219], v[130:133], v[82:97]
	ds_read_b128 v[216:219], v205 offset:26624
	s_waitcnt lgkmcnt(3)
	v_mfma_f32_32x32x16_bf16 v[82:97], v[238:241], v[138:141], v[82:97]
	ds_read_b128 v[238:241], v207 offset:26624
	v_sub_f32_e32 v64, v76, v211
	v_exp_f32_e32 v233, v64
	v_sub_f32_e32 v64, v77, v211
	v_exp_f32_e32 v234, v64
	v_sub_f32_e32 v64, v78, v211
	v_exp_f32_e32 v235, v64
	v_sub_f32_e32 v72, v79, v211
	v_exp_f32_e32 v236, v72
	s_waitcnt lgkmcnt(3)
	v_mfma_f32_32x32x16_bf16 v[82:97], v[242:245], v[134:137], v[82:97]
	ds_read_b128 v[242:245], v205 offset:35840
	s_waitcnt lgkmcnt(3)
	v_mfma_f32_32x32x16_bf16 v[82:97], v[246:249], v[142:145], v[82:97]
	ds_read_b128 v[246:249], v205 offset:40448
	v_cvt_pk_bf16_f32 v64, v212, v213
	v_cvt_pk_bf16_f32 v65, v214, v215
	v_cvt_pk_bf16_f32 v66, v225, v226
	v_cvt_pk_bf16_f32 v67, v227, v228
	v_cvt_pk_bf16_f32 v72, v229, v230
	v_cvt_pk_bf16_f32 v73, v231, v232
	v_cvt_pk_bf16_f32 v74, v233, v234
	v_cvt_pk_bf16_f32 v75, v235, v236
	ds_read_b128 v[68:71], v205 offset:26656
	ds_read_b128 v[76:79], v207 offset:26656
	s_waitcnt lgkmcnt(5)
	v_mfma_f32_32x32x16_bf16 v[0:15], v[64:67], v[216:219], v[0:15]
	ds_read_b128 v[216:219], v205 offset:35872
	s_waitcnt lgkmcnt(5)
	v_mfma_f32_32x32x16_bf16 v[16:31], v[64:67], v[238:241], v[16:31]
	ds_read_b128 v[238:241], v205 offset:40480
	s_waitcnt lgkmcnt(5)
	v_mfma_f32_32x32x16_bf16 v[32:47], v[64:67], v[242:245], v[32:47]
	s_waitcnt lgkmcnt(4)
	v_mfma_f32_32x32x16_bf16 v[48:63], v[64:67], v[246:249], v[48:63]
	s_andn2_b64 vcc, exec, s[0:1]
	s_cbranch_vccnz .LBB0_308
	v_add_u32_e32 v204, 32, v208
	v_cmp_le_i32_e32 vcc, v204, v174
	v_add_u32_e32 v204, 33, v208
	s_nop 0
	v_cndmask_b32_e32 v82, v223, v82, vcc
	v_cmp_le_i32_e32 vcc, v204, v174
	v_add_u32_e32 v204, 34, v208
	s_nop 0
	v_cndmask_b32_e32 v83, v223, v83, vcc
	v_cmp_le_i32_e32 vcc, v204, v174
	v_add_u32_e32 v204, 35, v208
	s_nop 0
	v_cndmask_b32_e32 v84, v223, v84, vcc
	v_cmp_le_i32_e32 vcc, v204, v174
	v_add_u32_e32 v204, 40, v208
	s_nop 0
	v_cndmask_b32_e32 v85, v223, v85, vcc
	v_cmp_le_i32_e32 vcc, v204, v174
	v_add_u32_e32 v204, 41, v208
	s_nop 0
	v_cndmask_b32_e32 v86, v223, v86, vcc
	v_cmp_le_i32_e32 vcc, v204, v174
	v_add_u32_e32 v204, 42, v208
	s_nop 0
	v_cndmask_b32_e32 v87, v223, v87, vcc
	v_cmp_le_i32_e32 vcc, v204, v174
	v_add_u32_e32 v204, 43, v208
	s_nop 0
	v_cndmask_b32_e32 v88, v223, v88, vcc
	v_cmp_le_i32_e32 vcc, v204, v174
	v_add_u32_e32 v204, 48, v208
	s_nop 0
	v_cndmask_b32_e32 v89, v223, v89, vcc
	v_cmp_le_i32_e32 vcc, v204, v174
	v_add_u32_e32 v204, 49, v208
	s_nop 0
	v_cndmask_b32_e32 v90, v223, v90, vcc
	v_cmp_le_i32_e32 vcc, v204, v174
	v_add_u32_e32 v204, 50, v208
	s_nop 0
	v_cndmask_b32_e32 v91, v223, v91, vcc
	v_cmp_le_i32_e32 vcc, v204, v174
	v_add_u32_e32 v204, 51, v208
	s_nop 0
	v_cndmask_b32_e32 v92, v223, v92, vcc
	v_cmp_le_i32_e32 vcc, v204, v174
	v_add_u32_e32 v204, 56, v208
	s_nop 0
	v_cndmask_b32_e32 v93, v223, v93, vcc
	v_cmp_le_i32_e32 vcc, v204, v174
	v_add_u32_e32 v204, 57, v208
	s_nop 0
	v_cndmask_b32_e32 v94, v223, v94, vcc
	v_cmp_le_i32_e32 vcc, v204, v174
	v_add_u32_e32 v204, 58, v208
	s_nop 0
	v_cndmask_b32_e32 v95, v223, v95, vcc
	v_cmp_le_i32_e32 vcc, v204, v174
	v_add_u32_e32 v204, 59, v208
	s_nop 0
	v_cndmask_b32_e32 v96, v223, v96, vcc
	v_cmp_le_i32_e32 vcc, v204, v174
	s_nop 1
	v_cndmask_b32_e32 v97, v223, v97, vcc

; #define LAS __attribute__((address_space(3)))
; DI int crow(int i, int hh) { return (i & 3) + 8 * (i >> 2) + 4 * hh; }
; #define MFMA32(a, b, c) __builtin_amdgcn_mfma_f32_32x32x16_bf16((a), (b), (c), 0, 0, 0)
; DI void attn_store(LAS unsigned char* lds, int tid, const u32x4 (&kr)[3], const u32x4 (&vr)[2]) {
;     LAS bf16_t* Ks = (LAS bf16_t*)(lds + AT_KS); LAS bf16_t* Rs = (LAS bf16_t*)(lds + AT_RS); LAS bf16_t* Vs = (LAS bf16_t*)(lds + AT_VS);
; #pragma unroll
;     for (int i = 0; i < 2; ++i) { const int ck = tid + 512 * i, row = ck >> 4, cc = ck & 15; *(LAS u32x4*)(Ks + row * 136 + 8 * cc) = kr[i]; }
;     { const int row = tid >> 3, cc = tid & 7; *(LAS u32x4*)(Rs + row * 72 + 8 * cc) = kr[2]; }
; #pragma unroll
;     for (int i = 0; i < 2; ++i) { const int cv = tid + 512 * i, v = cv >> 3, cc = cv & 7;
;         LAS bf16_t* d = Vs + v * 72 + 16 * (cc >> 1) + 4 * (cc & 1);
;         *(LAS u32x2*)d = (u32x2){vr[i].x, vr[i].y}; *(LAS u32x2*)(d + 8) = (u32x2){vr[i].z, vr[i].w}; }
; DI void attn_item(CArgs& a, LAS unsigned char* lds, int l, int b, int h, int qb, int tid_, int wave, int lane_) {
;     ...
;     for (int j = 0; j < NT; ++j) {
;         const int boff = (j & 1) * AT_BUF;
;         if (j + 1 < NT) attn_store(lds + (AT_BUF - boff), tid, kr, vr);
;         if (j + 2 < NT) attn_load(a, b, h, j + 2, F, kr, vr);
;         LAS bf16_t* Ks = (LAS bf16_t*)(lds + boff + AT_KS); LAS bf16_t* Rs = (LAS bf16_t*)(lds + boff + AT_RS); LAS bf16_t* Vs = (LAS bf16_t*)(lds + boff + AT_VS);
; #pragma unroll
;         for (int kt = 0; kt < 2; ++kt) {
;             f32x16 p = zero16();
; #pragma unroll
;             for (int ks = 0; ks < 8; ++ks) p = MFMA32(lds_b128(Ks + (32 * kt + r) * 136 + 16 * ks + 8 * hh), qf[ks], p);
; #pragma unroll
;             for (int ks = 0; ks < 4; ++ks) p = MFMA32(lds_b128(Rs + (32 * kt + r) * 72 + 16 * ks + 8 * hh), qf[8 + ks], p);
;             if (j >= 4 * qb) {
; #pragma unroll
;                 for (int i = 0; i < 16; ++i) { const int key = 64 * j + 32 * kt + crow(i, hh); if (key > qloc) p[i] = -INFINITY; } }
.LBB0_317:
	s_bitcmp1_b32 s2, 0
	s_cselect_b32 s0, 0xb000, 0
	s_add_i32 s17, s2, 1
	s_add_i32 s18, s0, 0
	v_add_u32_e32 v205, s18, v80
	v_add_u32_e32 v209, v205, v200
	v_add_u32_e32 v210, v205, v199
	ds_read_b128 v[212:215], v209
	ds_read_b128 v[226:229], v209 offset:32
	ds_read_b128 v[230:233], v209 offset:64
	ds_read_b128 v[234:237], v209 offset:96
	s_sub_i32 s100, 0, s0
	s_add_i32 s101, s100, 0xb000
	s_cmp_ge_u32 s2, s36
	s_cselect_b64 s[0:1], -1, 0
	s_cmp_lt_u32 s2, s36
	v_add_u32_e32 v208, s4, v195
	s_waitcnt lgkmcnt(3)
	v_mfma_f32_32x32x16_bf16 v[64:79], v[212:215], v[98:101], 0
	ds_read_b128 v[212:215], v209 offset:128
	s_waitcnt lgkmcnt(3)
	v_mfma_f32_32x32x16_bf16 v[64:79], v[226:229], v[102:105], v[64:79]
	ds_read_b128 v[226:229], v209 offset:160
	s_waitcnt lgkmcnt(3)
	v_mfma_f32_32x32x16_bf16 v[64:79], v[230:233], v[106:109], v[64:79]
	ds_read_b128 v[230:233], v209 offset:192
	s_waitcnt lgkmcnt(3)
	v_mfma_f32_32x32x16_bf16 v[64:79], v[234:237], v[110:113], v[64:79]
	ds_read_b128 v[234:237], v209 offset:224
	s_waitcnt lgkmcnt(3)
	v_mfma_f32_32x32x16_bf16 v[64:79], v[212:215], v[114:117], v[64:79]
	ds_read_b128 v[212:215], v210 offset:17408
	s_waitcnt lgkmcnt(3)
	v_mfma_f32_32x32x16_bf16 v[64:79], v[226:229], v[118:121], v[64:79]
	ds_read_b128 v[226:229], v210 offset:17440
	s_waitcnt lgkmcnt(3)
	v_mfma_f32_32x32x16_bf16 v[64:79], v[230:233], v[122:125], v[64:79]
	ds_read_b128 v[230:233], v210 offset:17472
	s_waitcnt lgkmcnt(3)
	v_mfma_f32_32x32x16_bf16 v[64:79], v[234:237], v[126:129], v[64:79]
	ds_read_b128 v[234:237], v210 offset:17504
	s_waitcnt lgkmcnt(3)
	v_mfma_f32_32x32x16_bf16 v[64:79], v[212:215], v[130:133], v[64:79]
	s_waitcnt lgkmcnt(2)
	v_mfma_f32_32x32x16_bf16 v[64:79], v[226:229], v[138:141], v[64:79]
	s_waitcnt lgkmcnt(1)
	v_mfma_f32_32x32x16_bf16 v[64:79], v[230:233], v[134:137], v[64:79]
	s_waitcnt lgkmcnt(0)
	v_mfma_f32_32x32x16_bf16 v[64:79], v[234:237], v[142:145], v[64:79]
	s_cmp_ge_u32 s17, s47
	s_cbranch_scc1 .LBB0_319
	v_lshl_add_u32 v230, v188, 1, s100
	v_add_u32_e32 v231, v230, v175
	v_add_u32_e32 v230, v230, v189
	s_waitcnt vmcnt(4)
	ds_write_b128 v231, v[146:149] offset:45056
	s_waitcnt vmcnt(3)
	ds_write_b128 v230, v[150:153] offset:45056
	v_add3_u32 v230, s100, v190, v191
	s_waitcnt vmcnt(2)
	ds_write_b128 v230, v[154:157] offset:62464
	v_add3_u32 v230, s101, v192, v193
	v_add_u32_e32 v231, v230, v190
	v_add_u32_e32 v230, v230, v194
	v_add_u32_e32 v231, 0x6800, v231
	v_add_u32_e32 v230, 0x6800, v230
	s_waitcnt vmcnt(1)
	ds_write2_b64 v231, v[158:159], v[160:161] offset1:2
	s_waitcnt vmcnt(0)
	ds_write2_b64 v230, v[162:163], v[164:165] offset1:2
.LBB0_319:
	s_add_i32 s100, s2, 2
	s_cmp_ge_u32 s100, s47
	s_cbranch_scc1 .LBB0_321
	v_lshl_add_u64 v[226:227], s[44:45], 0, v[182:183]
	v_lshl_add_u64 v[228:229], s[44:45], 0, v[184:185]
	global_load_dwordx4 v[146:149], v[226:227], off
	global_load_dwordx4 v[150:153], v[228:229], off
	v_lshl_add_u64 v[226:227], s[44:45], 0, v[180:181]
	v_lshl_add_u64 v[228:229], s[44:45], 0, v[176:177]
	global_load_dwordx4 v[154:157], v[226:227], off
	global_load_dwordx4 v[158:161], v[228:229], off
	v_lshl_add_u64 v[226:227], s[44:45], 0, v[178:179]
	global_load_dwordx4 v[162:165], v[226:227], off
.LBB0_321:
	ds_read_b128 v[216:219], v209 offset:8704
	ds_read_b128 v[238:241], v209 offset:8736
	ds_read_b128 v[242:245], v209 offset:8768
	ds_read_b128 v[246:249], v209 offset:8800
	s_nop 3
	s_cmp_lt_u32 s2, s36
	s_cbranch_scc1 .LBB0_323
	v_cmp_lt_i32_e32 vcc, v208, v174
	v_add_u32_e32 v205, 2, v208
	s_nop 0
	v_cndmask_b32_e32 v65, v223, v65, vcc
	v_cmp_le_i32_e32 vcc, v208, v174
	s_nop 1
	v_cndmask_b32_e32 v64, v223, v64, vcc
	v_cmp_le_i32_e32 vcc, v205, v174
	v_add_u32_e32 v205, 3, v208
	s_nop 0
	v_cndmask_b32_e32 v66, v223, v66, vcc
	v_cmp_le_i32_e32 vcc, v205, v174
	v_add_u32_e32 v205, 8, v208
	s_nop 0
	v_cndmask_b32_e32 v67, v223, v67, vcc
	v_cmp_le_i32_e32 vcc, v205, v174
	v_add_u32_e32 v205, 9, v208
	s_nop 0
	v_cndmask_b32_e32 v68, v223, v68, vcc
	v_cmp_le_i32_e32 vcc, v205, v174
	v_add_u32_e32 v205, 10, v208
	s_nop 0
	v_cndmask_b32_e32 v69, v223, v69, vcc
	v_cmp_le_i32_e32 vcc, v205, v174
	v_add_u32_e32 v205, 11, v208
	s_nop 0
	v_cndmask_b32_e32 v70, v223, v70, vcc
	v_cmp_le_i32_e32 vcc, v205, v174
	v_add_u32_e32 v205, 16, v208
	s_nop 0
	v_cndmask_b32_e32 v71, v223, v71, vcc
	v_cmp_le_i32_e32 vcc, v205, v174
	v_add_u32_e32 v205, 17, v208
	s_nop 0
	v_cndmask_b32_e32 v72, v223, v72, vcc
	v_cmp_le_i32_e32 vcc, v205, v174
	v_add_u32_e32 v205, 18, v208
	s_nop 0
	v_cndmask_b32_e32 v73, v223, v73, vcc
	v_cmp_le_i32_e32 vcc, v205, v174
	v_add_u32_e32 v205, 19, v208
	s_nop 0
	v_cndmask_b32_e32 v74, v223, v74, vcc
	v_cmp_le_i32_e32 vcc, v205, v174
	v_add_u32_e32 v205, 24, v208
	s_nop 0
	v_cndmask_b32_e32 v75, v223, v75, vcc
	v_cmp_le_i32_e32 vcc, v205, v174
	v_add_u32_e32 v205, 25, v208
	s_nop 0
	v_cndmask_b32_e32 v76, v223, v76, vcc
	v_cmp_le_i32_e32 vcc, v205, v174
	v_add_u32_e32 v205, 26, v208
	s_nop 0
	v_cndmask_b32_e32 v77, v223, v77, vcc
	v_cmp_le_i32_e32 vcc, v205, v174
	v_add_u32_e32 v205, 27, v208
	s_nop 0
	v_cndmask_b32_e32 v78, v223, v78, vcc
	v_cmp_le_i32_e32 vcc, v205, v174
	s_nop 1
	v_cndmask_b32_e32 v79, v223, v79, vcc
; DI float shx(float v, int o, int lane) { return __int_as_float(__builtin_amdgcn_ds_bpermute((lane ^ o) << 2, __float_as_int(v))); }
; DI int crow(int i, int hh) { return (i & 3) + 8 * (i >> 2) + 4 * hh; }
; DI void attn_item(CArgs& a, LAS unsigned char* lds, int l, int b, int h, int qb, int tid_, int wave, int lane_) {
;     ...
;             float tmax = p[0];
; #pragma unroll
;             for (int i = 1; i < 16; ++i) tmax = fmaxf(tmax, p[i]);
;             tmax = fmaxf(tmax, shx(tmax, 32, lane));
;             const float m_new = fmaxf(m_run, tmax), alpha = __builtin_amdgcn_exp2f(m_run - m_new); m_run = m_new;
;             float rsum = 0.f;
; #pragma unroll
;             for (int i = 0; i < 16; ++i) { const float e = __builtin_amdgcn_exp2f(p[i] - m_new); p[i] = e; rsum += e; }
;             l_run = l_run * alpha + rsum;
;             if (__any(alpha != 1.f)) {
;                 if (hh == 0) scr[r] = alpha;
;                 asm volatile("s_waitcnt lgkmcnt(0)" ::: "memory");
; #pragma unroll
;                 for (int i = 0; i < 16; ++i) { const float ai = scr[crow(i, hh)]; o[0][i] *= ai; o[1][i] *= ai; o[2][i] *= ai; o[3][i] *= ai; }
;             }
.LBB0_323:
	v_max_f32_e32 v205, v65, v65
	v_max_f32_e32 v206, v64, v64
	v_max_f32_e32 v205, v206, v205
	v_max3_f32 v205, v205, v66, v67
	v_max3_f32 v205, v205, v68, v69
	v_max3_f32 v205, v205, v70, v71
	v_max3_f32 v205, v205, v72, v73
	v_max3_f32 v205, v205, v74, v75
	v_max3_f32 v205, v205, v76, v77
	v_max3_f32 v205, v205, v78, v79
	ds_bpermute_b32 v206, v198, v205
	s_waitcnt lgkmcnt(4)
	v_mfma_f32_32x32x16_bf16 v[82:97], v[216:219], v[98:101], 0
	ds_read_b128 v[216:219], v209 offset:8832
	s_waitcnt lgkmcnt(4)
	v_mfma_f32_32x32x16_bf16 v[82:97], v[238:241], v[102:105], v[82:97]
	ds_read_b128 v[238:241], v209 offset:8864
	s_waitcnt lgkmcnt(2)
	v_max3_f32 v211, v204, v205, v206
	v_sub_f32_e32 v204, v204, v211
	v_exp_f32_e32 v206, v204
	s_nop 0
	v_cmp_neq_f32_e32 vcc, 1.0, v206
	s_cbranch_vccz .LBB0_327
	s_and_saveexec_b64 s[2:3], s[6:7]
	ds_write_b32 v197, v206
	s_or_b64 exec, exec, s[2:3]
	s_waitcnt lgkmcnt(0)
	v_add_u32_e32 v204, s27, v80
	ds_read_b128 v[212:215], v204 offset:96
	ds_read_b128 v[234:237], v204 offset:64
	ds_read_b128 v[226:229], v204 offset:32
	ds_read_b128 v[230:233], v204
	s_waitcnt lgkmcnt(3)
	v_pk_mul_f32 v[12:13], v[12:13], v[212:213]
	s_waitcnt lgkmcnt(2)
	v_pk_mul_f32 v[8:9], v[8:9], v[234:235]
	s_waitcnt lgkmcnt(1)
	v_pk_mul_f32 v[4:5], v[4:5], v[226:227]
	v_pk_mul_f32 v[14:15], v[14:15], v[214:215]
	v_pk_mul_f32 v[10:11], v[10:11], v[236:237]
	v_pk_mul_f32 v[6:7], v[6:7], v[228:229]
	s_waitcnt lgkmcnt(0)
	v_pk_mul_f32 v[2:3], v[2:3], v[232:233]
	v_pk_mul_f32 v[0:1], v[0:1], v[230:231]
	v_pk_mul_f32 v[28:29], v[28:29], v[212:213]
	v_pk_mul_f32 v[24:25], v[24:25], v[234:235]
	v_pk_mul_f32 v[20:21], v[20:21], v[226:227]
	v_pk_mul_f32 v[30:31], v[30:31], v[214:215]
	v_pk_mul_f32 v[26:27], v[26:27], v[236:237]
	v_pk_mul_f32 v[22:23], v[22:23], v[228:229]
	v_pk_mul_f32 v[18:19], v[18:19], v[232:233]
	v_pk_mul_f32 v[16:17], v[16:17], v[230:231]
	v_pk_mul_f32 v[44:45], v[44:45], v[212:213]
	v_pk_mul_f32 v[40:41], v[40:41], v[234:235]
	v_pk_mul_f32 v[36:37], v[36:37], v[226:227]
	v_pk_mul_f32 v[46:47], v[46:47], v[214:215]
	v_pk_mul_f32 v[42:43], v[42:43], v[236:237]
	v_pk_mul_f32 v[38:39], v[38:39], v[228:229]
	v_pk_mul_f32 v[34:35], v[34:35], v[232:233]
	v_pk_mul_f32 v[32:33], v[32:33], v[230:231]
	v_pk_mul_f32 v[60:61], v[60:61], v[212:213]
	v_pk_mul_f32 v[56:57], v[56:57], v[234:235]
	v_pk_mul_f32 v[52:53], v[52:53], v[226:227]
	v_pk_mul_f32 v[62:63], v[62:63], v[214:215]
	v_pk_mul_f32 v[58:59], v[58:59], v[236:237]
	v_pk_mul_f32 v[54:55], v[54:55], v[228:229]
	v_pk_mul_f32 v[50:51], v[50:51], v[232:233]
	v_pk_mul_f32 v[48:49], v[48:49], v[230:231]
; DI float shx(float v, int o, int lane) { return __int_as_float(__builtin_amdgcn_ds_bpermute((lane ^ o) << 2, __float_as_int(v))); }
; DI int crow(int i, int hh) { return (i & 3) + 8 * (i >> 2) + 4 * hh; }
; #define MFMA32(a, b, c) __builtin_amdgcn_mfma_f32_32x32x16_bf16((a), (b), (c), 0, 0, 0)
; DI void attn_item(CArgs& a, LAS unsigned char* lds, int l, int b, int h, int qb, int tid_, int wave, int lane_) {
;     ...
;         for (int kt = 0; kt < 2; ++kt) {
;             f32x16 p = zero16();
; #pragma unroll
;             for (int ks = 0; ks < 8; ++ks) p = MFMA32(lds_b128(Ks + (32 * kt + r) * 136 + 16 * ks + 8 * hh), qf[ks], p);
; #pragma unroll
;             for (int ks = 0; ks < 4; ++ks) p = MFMA32(lds_b128(Rs + (32 * kt + r) * 72 + 16 * ks + 8 * hh), qf[8 + ks], p);
;             if (j >= 4 * qb) {
; #pragma unroll
;                 for (int i = 0; i < 16; ++i) { const int key = 64 * j + 32 * kt + crow(i, hh); if (key > qloc) p[i] = -INFINITY; } }
;             float tmax = p[0];
; #pragma unroll
;             for (int i = 1; i < 16; ++i) tmax = fmaxf(tmax, p[i]);
;             tmax = fmaxf(tmax, shx(tmax, 32, lane));
;             const float m_new = fmaxf(m_run, tmax), alpha = __builtin_amdgcn_exp2f(m_run - m_new); m_run = m_new;
;             float rsum = 0.f;
; #pragma unroll
;             for (int i = 0; i < 16; ++i) { const float e = __builtin_amdgcn_exp2f(p[i] - m_new); p[i] = e; rsum += e; }
;             l_run = l_run * alpha + rsum;
;             if (__any(alpha != 1.f)) {
;                 if (hh == 0) scr[r] = alpha;
;                 asm volatile("s_waitcnt lgkmcnt(0)" ::: "memory");
; #pragma unroll
;                 for (int i = 0; i < 16; ++i) { const float ai = scr[crow(i, hh)]; o[0][i] *= ai; o[1][i] *= ai; o[2][i] *= ai; o[3][i] *= ai; }
;             }
;             const bf16x8 pa0 = packstep<0>(p), pa1 = packstep<1>(p);
; #pragma unroll
;             for (int vt = 0; vt < 4; ++vt) {
;                 o[vt] = MFMA32(pa0, lds_b128(Vs + (32 * vt + r) * 72 + 32 * kt + 8 * hh), o[vt]);
;                 o[vt] = MFMA32(pa1, lds_b128(Vs + (32 * vt + r) * 72 + 32 * kt + 16 + 8 * hh), o[vt]); }
.LBB0_327:
	v_add3_u32 v205, s18, v199, v202
	v_add3_u32 v207, s18, v201, v202
	s_waitcnt lgkmcnt(4)
	v_mfma_f32_32x32x16_bf16 v[82:97], v[242:245], v[106:109], v[82:97]
	ds_read_b128 v[242:245], v209 offset:8896
	s_waitcnt lgkmcnt(4)
	v_mfma_f32_32x32x16_bf16 v[82:97], v[246:249], v[110:113], v[82:97]
	ds_read_b128 v[246:249], v209 offset:8928
	v_sub_f32_e32 v64, v64, v211
	v_exp_f32_e32 v212, v64
	v_sub_f32_e32 v64, v65, v211
	v_exp_f32_e32 v213, v64
	v_sub_f32_e32 v64, v66, v211
	v_exp_f32_e32 v214, v64
	v_sub_f32_e32 v64, v67, v211
	v_exp_f32_e32 v215, v64
	s_waitcnt lgkmcnt(3)
	v_mfma_f32_32x32x16_bf16 v[82:97], v[216:219], v[114:117], v[82:97]
	ds_read_b128 v[216:219], v210 offset:22016
	s_waitcnt lgkmcnt(3)
	v_mfma_f32_32x32x16_bf16 v[82:97], v[238:241], v[118:121], v[82:97]
	ds_read_b128 v[238:241], v210 offset:22048
	v_sub_f32_e32 v64, v68, v211
	v_exp_f32_e32 v225, v64
	v_sub_f32_e32 v64, v69, v211
	v_exp_f32_e32 v226, v64
	v_sub_f32_e32 v64, v70, v211
	v_exp_f32_e32 v227, v64
	v_sub_f32_e32 v64, v71, v211
	v_exp_f32_e32 v228, v64
	s_waitcnt lgkmcnt(3)
	v_mfma_f32_32x32x16_bf16 v[82:97], v[242:245], v[122:125], v[82:97]
	ds_read_b128 v[242:245], v210 offset:22080
	s_waitcnt lgkmcnt(3)
	v_mfma_f32_32x32x16_bf16 v[82:97], v[246:249], v[126:129], v[82:97]
	ds_read_b128 v[246:249], v210 offset:22112
	v_sub_f32_e32 v64, v72, v211
	v_exp_f32_e32 v229, v64
	v_sub_f32_e32 v64, v73, v211
	v_exp_f32_e32 v230, v64
	v_sub_f32_e32 v64, v74, v211
	v_exp_f32_e32 v231, v64
	v_sub_f32_e32 v64, v75, v211
	v_exp_f32_e32 v232, v64
	s_waitcnt lgkmcnt(3)
	v_mfma_f32_32x32x16_bf16 v[82:97], v[216:219], v[130:133], v[82:97]
	ds_read_b128 v[216:219], v205 offset:26624
	s_waitcnt lgkmcnt(3)
	v_mfma_f32_32x32x16_bf16 v[82:97], v[238:241], v[138:141], v[82:97]
	ds_read_b128 v[238:241], v207 offset:26624
	v_sub_f32_e32 v64, v76, v211
	v_exp_f32_e32 v233, v64
	v_sub_f32_e32 v64, v77, v211
	v_exp_f32_e32 v234, v64
	v_sub_f32_e32 v64, v78, v211
	v_exp_f32_e32 v235, v64
	v_sub_f32_e32 v72, v79, v211
	v_exp_f32_e32 v236, v72
	s_waitcnt lgkmcnt(3)
	v_mfma_f32_32x32x16_bf16 v[82:97], v[242:245], v[134:137], v[82:97]
	ds_read_b128 v[242:245], v205 offset:35840
	s_waitcnt lgkmcnt(3)
	v_mfma_f32_32x32x16_bf16 v[82:97], v[246:249], v[142:145], v[82:97]
	ds_read_b128 v[246:249], v205 offset:40448
	v_cvt_pk_bf16_f32 v64, v212, v213
	v_cvt_pk_bf16_f32 v65, v214, v215
	v_cvt_pk_bf16_f32 v66, v225, v226
	v_cvt_pk_bf16_f32 v67, v227, v228
	v_cvt_pk_bf16_f32 v72, v229, v230
	v_cvt_pk_bf16_f32 v73, v231, v232
	v_cvt_pk_bf16_f32 v74, v233, v234
	v_cvt_pk_bf16_f32 v75, v235, v236
	ds_read_b128 v[68:71], v205 offset:26656
	ds_read_b128 v[76:79], v207 offset:26656
	s_waitcnt lgkmcnt(5)
	v_mfma_f32_32x32x16_bf16 v[0:15], v[64:67], v[216:219], v[0:15]
	ds_read_b128 v[216:219], v205 offset:35872
	s_waitcnt lgkmcnt(5)
	v_mfma_f32_32x32x16_bf16 v[16:31], v[64:67], v[238:241], v[16:31]
	ds_read_b128 v[238:241], v205 offset:40480
	s_waitcnt lgkmcnt(5)
	v_mfma_f32_32x32x16_bf16 v[32:47], v[64:67], v[242:245], v[32:47]
	s_waitcnt lgkmcnt(4)
	v_mfma_f32_32x32x16_bf16 v[48:63], v[64:67], v[246:249], v[48:63]
	s_andn2_b64 vcc, exec, s[0:1]
	s_cbranch_vccnz .LBB0_329
	v_add_u32_e32 v204, 32, v208
	v_cmp_le_i32_e32 vcc, v204, v174
	v_add_u32_e32 v204, 33, v208
	s_nop 0
	v_cndmask_b32_e32 v82, v223, v82, vcc
	v_cmp_le_i32_e32 vcc, v204, v174
	v_add_u32_e32 v204, 34, v208
	s_nop 0
	v_cndmask_b32_e32 v83, v223, v83, vcc
	v_cmp_le_i32_e32 vcc, v204, v174
	v_add_u32_e32 v204, 35, v208
	s_nop 0
	v_cndmask_b32_e32 v84, v223, v84, vcc
	v_cmp_le_i32_e32 vcc, v204, v174
	v_add_u32_e32 v204, 40, v208
	s_nop 0
	v_cndmask_b32_e32 v85, v223, v85, vcc
	v_cmp_le_i32_e32 vcc, v204, v174
	v_add_u32_e32 v204, 41, v208
	s_nop 0
	v_cndmask_b32_e32 v86, v223, v86, vcc
	v_cmp_le_i32_e32 vcc, v204, v174
	v_add_u32_e32 v204, 42, v208
	s_nop 0
	v_cndmask_b32_e32 v87, v223, v87, vcc
	v_cmp_le_i32_e32 vcc, v204, v174
	v_add_u32_e32 v204, 43, v208
	s_nop 0
	v_cndmask_b32_e32 v88, v223, v88, vcc
	v_cmp_le_i32_e32 vcc, v204, v174
	v_add_u32_e32 v204, 48, v208
	s_nop 0
	v_cndmask_b32_e32 v89, v223, v89, vcc
	v_cmp_le_i32_e32 vcc, v204, v174
	v_add_u32_e32 v204, 49, v208
	s_nop 0
	v_cndmask_b32_e32 v90, v223, v90, vcc
	v_cmp_le_i32_e32 vcc, v204, v174
	v_add_u32_e32 v204, 50, v208
	s_nop 0
	v_cndmask_b32_e32 v91, v223, v91, vcc
	v_cmp_le_i32_e32 vcc, v204, v174
	v_add_u32_e32 v204, 51, v208
	s_nop 0
	v_cndmask_b32_e32 v92, v223, v92, vcc
	v_cmp_le_i32_e32 vcc, v204, v174
	v_add_u32_e32 v204, 56, v208
	s_nop 0
	v_cndmask_b32_e32 v93, v223, v93, vcc
	v_cmp_le_i32_e32 vcc, v204, v174
	v_add_u32_e32 v204, 57, v208
	s_nop 0
	v_cndmask_b32_e32 v94, v223, v94, vcc
	v_cmp_le_i32_e32 vcc, v204, v174
	v_add_u32_e32 v204, 58, v208
	s_nop 0
	v_cndmask_b32_e32 v95, v223, v95, vcc
	v_cmp_le_i32_e32 vcc, v204, v174
	v_add_u32_e32 v204, 59, v208
	s_nop 0
	v_cndmask_b32_e32 v96, v223, v96, vcc
	v_cmp_le_i32_e32 vcc, v204, v174
	s_nop 1
	v_cndmask_b32_e32 v97, v223, v97, vcc
